# retention tile loop edges: loop-control scalar updates moved ahead of the tile barrier, weight-conversion load block and the last-tile wait moved out of line so the common path falls through
# baseline (speedup 1.0000x reference)
; #define RT_BAR() do { asm volatile("s_waitcnt lgkmcnt(0)" ::: "memory"); __builtin_amdgcn_s_barrier(); asm volatile("" ::: "memory"); } while (0)
; __device__ __forceinline__ void p2_ret(const Frame& F, ArgsP a, int layer) {
;     ...
;                 const bool cv = cvhi < CV_HALF_ITEMS && ((cvtile++ & 1) == 0); f32x4 cvv[8], cvsc[2];
;                 if (cv) { const CvU cu = cv_decode(a, F.ws, cvhi, layer); cv_load(cu, lane, cvv, cvsc); }
;     ...
;                 asm volatile("s_waitcnt vmcnt(0)" ::: "memory");
;                 if (cv) { const CvU cu = cv_decode(a, F.ws, cvhi, layer); cv_store(cu, lane, cvv, cvsc); cvhi += cvs; }
;                 RT_BAR();
;             }
.LBB0_357:
	s_cmp_lg_u64 s[2:3], 0
	s_addc_u32 s37, s37, 0
	s_sub_i32 s97, s97, 64
	s_addk_i32 s30, 0x80
	s_add_i32 s31, s31, 0x8000
	s_add_i32 s27, s27, 0x40000
	s_add_i32 s91, s91, 1
	s_cmp_eq_u32 s11, s30
	s_waitcnt lgkmcnt(0)
	s_barrier
	s_cbranch_scc1 .LBB0_410
.LBB0_358:
	s_cmp_lt_i32 s36, s93
	s_cselect_b64 s[2:3], -1, 0
	s_bitcmp0_b32 s37, 0
	s_cselect_b64 s[4:5], -1, 0
	s_and_b64 s[4:5], s[2:3], s[4:5]
	s_not_b64 s[38:39], s[4:5]
	s_andn2_b64 vcc, exec, s[4:5]
	s_cbranch_vccz .Lcv_top

; #define LAS __attribute__((address_space(3)))
; #define RT_BAR() do { asm volatile("s_waitcnt lgkmcnt(0)" ::: "memory"); __builtin_amdgcn_s_barrier(); asm volatile("" ::: "memory"); } while (0)
; #define RT_VRD(dst, g) do { _Pragma("unroll") for (int j_ = 0; j_ < 2; ++j_) { const int jj_ = 2 * ((g) & 1) + j_; dst[j_] = *(const LAS bf16x8*)(vb + ((g) >> 1) * 4096 + (((4 * (jj_ >> 1) + 2 * (jj_ & 1) + hh) << 4) ^ m4)); } } while (0)
; #define RT_VMM(src, g) do { _Pragma("unroll") for (int j_ = 0; j_ < 2; ++j_) { const int jj_ = 2 * ((g) & 1) + j_; oacc[(g) >> 1] = __builtin_amdgcn_mfma_f32_32x32x16_bf16(src[j_], pf[jj_ >> 1][jj_ & 1], oacc[(g) >> 1], 0, 0, 0); } } while (0)
; __device__ __forceinline__ void p2_ret(const Frame& F, ArgsP a, int layer) {
;     ...
;                 { bf16x8 pf[2][2];
; #pragma unroll
;                   for (int kb2 = 0; kb2 < 2; ++kb2)
; #pragma unroll
;                       for (int s = 0; s < 2; ++s) pf[kb2][s] = *(const LAS bf16x8*)(lds + RT_P + ((wr * 2 + kb2) * 2 + s) * 1024 + lane * 16);
;                   const LAS unsigned char* vb = lds + RT_V0 + bf * 32768 + (128 * wc + kap) * 128;
;     ...
;                   bf16x8 va[2], vc[2];
;                   RT_VRD(va, 0); __builtin_amdgcn_sched_barrier(0);
;                   RT_VRD(vc, 1); RT_VMM(va, 0); __builtin_amdgcn_sched_barrier(0);
;                   RT_VRD(va, 2); RT_VMM(vc, 1); __builtin_amdgcn_sched_barrier(0);
;                   RT_VRD(vc, 3); RT_VMM(va, 2); __builtin_amdgcn_sched_barrier(0);
;                   RT_VRD(va, 4); RT_VMM(vc, 3); __builtin_amdgcn_sched_barrier(0);
;                   RT_VRD(vc, 5); RT_VMM(va, 4); __builtin_amdgcn_sched_barrier(0);
;                   RT_VRD(va, 6); RT_VMM(vc, 5); __builtin_amdgcn_sched_barrier(0);
;                   RT_VRD(vc, 7); RT_VMM(va, 6); __builtin_amdgcn_sched_barrier(0);
;                   RT_VMM(vc, 7); __builtin_amdgcn_sched_barrier(0);
;     ...
;                 }
;                 asm volatile("s_waitcnt vmcnt(0)" ::: "memory");
;                 if (cv) { const CvU cu = cv_decode(a, F.ws, cvhi, layer); cv_store(cu, lane, cvv, cvsc); cvhi += cvs; }
;                 RT_BAR();
.Lrk_skip:
	s_waitcnt lgkmcnt(5)
	v_mfma_f32_32x32x16_bf16 v[34:49], v[242:245], v[190:193], v[34:49]
	s_waitcnt lgkmcnt(4)
	v_mfma_f32_32x32x16_bf16 v[34:49], v[106:109], v[194:197], v[34:49]
	ds_read_b128 v[242:245], v248 offset:4096
	ds_read_b128 v[106:109], v249 offset:4096
	s_waitcnt lgkmcnt(2)
	v_mfma_f32_32x32x16_bf16 v[82:97], v[234:237], v[98:101], v[82:97]
	v_mfma_f32_32x32x16_bf16 v[82:97], v[238:241], v[102:105], v[82:97]
	ds_read_b128 v[234:237], v248 offset:8192
	ds_read_b128 v[238:241], v249 offset:8192
	s_waitcnt lgkmcnt(3)
	v_mfma_f32_32x32x16_bf16 v[66:81], v[242:245], v[98:101], v[66:81]
	s_waitcnt lgkmcnt(2)
	v_mfma_f32_32x32x16_bf16 v[66:81], v[106:109], v[102:105], v[66:81]
	ds_read_b128 v[242:245], v248 offset:12288
	ds_read_b128 v[106:109], v249 offset:12288
	s_waitcnt lgkmcnt(3)
	v_mfma_f32_32x32x16_bf16 v[50:65], v[234:237], v[98:101], v[50:65]
	s_waitcnt lgkmcnt(2)
	v_mfma_f32_32x32x16_bf16 v[50:65], v[238:241], v[102:105], v[50:65]
	s_waitcnt lgkmcnt(1)
	v_mfma_f32_32x32x16_bf16 v[34:49], v[242:245], v[98:101], v[34:49]
	s_waitcnt lgkmcnt(0)
	v_mfma_f32_32x32x16_bf16 v[34:49], v[106:109], v[102:105], v[34:49]
	s_add_i32 s12, s30, 0x80
	s_cmp_eq_u32 s12, s11
	s_cbranch_scc1 .Lrk_w0
	s_waitcnt vmcnt(4)
.Lrk_wd:
	s_and_b64 vcc, exec, s[38:39]
	s_cbranch_vccnz .LBB0_357
	s_ashr_i32 s14, s36, 1
	s_cmpk_lt_i32 s14, 0x400
	s_cselect_b64 s[4:5], -1, 0
	s_mov_b64 s[70:71], 0
	s_and_b64 vcc, exec, s[4:5]
	s_cbranch_vccnz .LBB0_394
	s_mov_b64 s[46:47], -1
	s_cmpk_gt_u32 s14, 0x13ff
	s_mov_b64 s[6:7], -1
	s_cbranch_scc0 .LBB0_391
	s_add_i32 s12, s14, 0xffffec00
	s_mov_b64 s[6:7], 0

; __device__ __forceinline__ CvU cv_decode(ArgsP a, unsigned char* ws, int hi, int layer) {
;     CvU u; int fi = hi >> 1; const int half = hi & 1; int l = layer, kind;
;     if (fi < CV_GLU) kind = 0; else if ((fi -= CV_GLU) < CV_OUT) kind = 1; else { fi -= CV_OUT; kind = 2; l = layer + 1; }
;     int kb, nb;
;     if (kind == 0) { u.W = a->in[I_WGLU] + (size_t)l * DS * DS; u.WT = (bf16_t*)(ws + WS_WTGLU + (size_t)l * DS * DS); u.K = DS; u.N = DS; kb = fi / (DS / 64); nb = fi % (DS / 64); }
;     else if (kind == 1) { u.W = a->in[I_WOUT] + (size_t)l * DM * DM; u.WT = (bf16_t*)(ws + WS_WTOUT) + (size_t)l * DM * DM; u.K = DM; u.N = DM; kb = fi / (DM / 64); nb = fi % (DM / 64); }
;     else { u.W = a->in[I_WIN] + (size_t)l * DM * NPROJ; u.WT = (bf16_t*)(ws + WS_WTIN) + (size_t)l * NPROJ * DM; u.K = DM; u.N = NPROJ; kb = fi / (NPROJ / 64); nb = fi % (NPROJ / 64); }
;     u.k0 = 64 * kb + 32 * half; u.n0 = 64 * nb; u.n0d = u.n0; u.rowperm = 0;
.Lcv_top:
	s_ashr_i32 s15, s36, 1
	s_cmpk_gt_i32 s15, 0x3ff
	s_cselect_b64 s[6:7], -1, 0
	s_cmpk_lt_i32 s15, 0x400
	s_mov_b64 s[70:71], 0
	s_cbranch_scc1 .LBB0_365
	s_mov_b64 s[4:5], -1
	s_cmpk_gt_u32 s15, 0x13ff
	s_mov_b64 s[12:13], -1
	s_cbranch_scc0 .LBB0_362
	s_add_i32 s14, s15, 0xffffec00
	s_mov_b64 s[12:13], 0

; __device__ __forceinline__ void cv_load(const CvU& u, int lane, f32x4 (&v)[8], f32x4 (&sc)[2]) {
;     const int nq = lane & 15, kq = lane >> 4;
;     const float* wp = u.W + (size_t)(u.k0 + 8 * kq) * u.N + u.n0 + 4 * nq;
; #pragma unroll
;     for (int i = 0; i < 8; ++i) v[i] = __builtin_nontemporal_load((const f32x4*)(wp + (size_t)i * u.N));
;     if (u.ks) { sc[0] = *(const f32x4*)(u.ks + 8 * kq); sc[1] = *(const f32x4*)(u.ks + 8 * kq + 4); }
;     else { sc[0] = (f32x4){1.f, 1.f, 1.f, 1.f}; sc[1] = sc[0]; }
; }
.LBB0_382:
	v_mov_b32_e32 v116, v114
	v_mov_b32_e32 v117, v114
	v_mov_b32_e32 v115, v114
	v_mov_b64_e32 v[184:185], v[116:117]
	v_mov_b64_e32 v[188:189], v[116:117]
	v_mov_b64_e32 v[182:183], v[114:115]
	v_mov_b64_e32 v[186:187], v[114:115]
	s_branch .LBB0_383
